# loop-edge: MLA step-tail rescale test chain shortened (two canonicalising v_max dropped, first v_max3 issued one MFMA earlier)
# speedup vs baseline: 1.0031x; 1.0031x over previous
.LBB0_1300:
	v_exp_f32_e32 v66, v66
	v_exp_f32_e32 v67, v67
	s_addk_i32 s16, 0xdc00
	s_cmp_lg_u32 s18, 0
	s_cselect_b32 s16, s16, 0x4800
	v_add_f32_e32 v98, v66, v67
	v_cvt_pk_bf16_f32 v66, v66, v67
	v_exp_f32_e32 v67, v68
	v_exp_f32_e32 v68, v69
	v_add_f32_e32 v98, 0, v98
	v_add_f32_e32 v69, v67, v68
	v_cvt_pk_bf16_f32 v67, v67, v68
	v_exp_f32_e32 v68, v70
	v_exp_f32_e32 v70, v71
	v_add_f32_e32 v69, v69, v98
	v_add_f32_e32 v71, v68, v70
	v_add_f32_e32 v69, v71, v69
	v_cvt_pk_bf16_f32 v68, v68, v70
	v_exp_f32_e32 v70, v72
	v_exp_f32_e32 v71, v73
	s_nop 0
	v_add_f32_e32 v72, v70, v71
	v_add_f32_e32 v72, v72, v69
	v_cvt_pk_bf16_f32 v69, v70, v71
	v_exp_f32_e32 v70, v74
	v_exp_f32_e32 v71, v75
	s_nop 0
	v_add_f32_e32 v73, v70, v71
	v_add_f32_e32 v72, v73, v72
	v_cvt_pk_bf16_f32 v70, v70, v71
	v_exp_f32_e32 v71, v76
	v_exp_f32_e32 v73, v77
	s_nop 0
	v_add_f32_e32 v74, v71, v73
	v_add_f32_e32 v72, v74, v72
	v_cvt_pk_bf16_f32 v71, v71, v73
	v_exp_f32_e32 v73, v78
	v_exp_f32_e32 v74, v79
	s_nop 0
	v_add_f32_e32 v75, v73, v74
	v_add_f32_e32 v75, v75, v72
	v_cvt_pk_bf16_f32 v72, v73, v74
	v_exp_f32_e32 v73, v80
	v_exp_f32_e32 v74, v81
	s_nop 0
	v_add_f32_e32 v76, v73, v74
	v_add_f32_e32 v75, v76, v75
	v_cvt_pk_bf16_f32 v73, v73, v74
	v_lshl_add_u32 v74, s16, 1, v210
	v_add_f32_e32 v98, v225, v75
	v_add_u32_e32 v225, 0xc800, v74
	v_add_u32_e32 v227, 0xc810, v74
	v_add_u32_e32 v232, 0xc820, v74
	v_add_u32_e32 v233, 0xc830, v74
	ds_read_b64 v[74:75], v225
	ds_read_b64 v[76:77], v227
	ds_read_b64 v[78:79], v225 offset:2304
	ds_read_b64 v[80:81], v227 offset:2304
	s_waitcnt lgkmcnt(2)
	v_mfma_f32_32x32x16_bf16 v[50:65], v[74:77], v[66:69], v[50:65]
	ds_read_b64 v[228:229], v225 offset:4608
	ds_read_b64 v[230:231], v227 offset:4608
	v_max3_f32 v234, v82, s39, v83
	s_waitcnt lgkmcnt(2)
	v_mfma_f32_32x32x16_bf16 v[34:49], v[78:81], v[66:69], v[34:49]
	ds_read_b64 v[74:75], v225 offset:6912
	ds_read_b64 v[76:77], v227 offset:6912
	v_max3_f32 v225, v234, v84, v85
	s_waitcnt lgkmcnt(2)
	v_mfma_f32_32x32x16_bf16 v[18:33], v[228:231], v[66:69], v[18:33]
	ds_read_b64 v[78:79], v232
	ds_read_b64 v[80:81], v233
	v_max3_f32 v225, v225, v86, v87
	s_waitcnt lgkmcnt(2)
	v_mfma_f32_32x32x16_bf16 v[2:17], v[74:77], v[66:69], v[2:17]
	ds_read_b64 v[228:229], v232 offset:2304
	ds_read_b64 v[230:231], v233 offset:2304
	v_max3_f32 v74, v225, v88, v89
	s_waitcnt lgkmcnt(2)
	v_mfma_f32_32x32x16_bf16 v[50:65], v[78:81], v[70:73], v[50:65]
	ds_read_b64 v[66:67], v232 offset:4608
	ds_read_b64 v[68:69], v233 offset:4608
	v_max3_f32 v78, v74, v90, v91
	s_waitcnt lgkmcnt(2)
	v_mfma_f32_32x32x16_bf16 v[34:49], v[228:231], v[70:73], v[34:49]
	ds_read_b64 v[74:75], v232 offset:6912
	ds_read_b64 v[76:77], v233 offset:6912
	s_waitcnt lgkmcnt(2)
	v_mfma_f32_32x32x16_bf16 v[18:33], v[66:69], v[70:73], v[18:33]
	v_max3_f32 v66, v78, v92, v93
	s_waitcnt lgkmcnt(0)
	v_mfma_f32_32x32x16_bf16 v[2:17], v[74:77], v[70:73], v[2:17]
	v_max3_f32 v66, v66, v94, v95
	v_max3_f32 v66, v66, v96, v97
	v_mov_b32_e32 v67, v66
	s_nop 1
	v_permlane32_swap_b32_e32 v66, v67
	v_max_f32_e32 v66, v66, v67
	v_cmp_lt_f32_e32 vcc, s26, v66
	s_cbranch_vccz .LBB0_1302
	v_max_f32_e32 v66, v66, v66
	v_max_f32_e32 v67, 0, v66
	v_exp_f32_e64 v66, -v67
	v_add_f32_e32 v1, v1, v67
	v_sub_f32_e32 v97, v97, v67
	v_sub_f32_e32 v96, v96, v67
	v_pk_mul_f32 v[64:65], v[64:65], v[66:67] op_sel_hi:[1,0]
	v_pk_mul_f32 v[62:63], v[62:63], v[66:67] op_sel_hi:[1,0]
	v_pk_mul_f32 v[60:61], v[60:61], v[66:67] op_sel_hi:[1,0]
	v_pk_mul_f32 v[58:59], v[58:59], v[66:67] op_sel_hi:[1,0]
	v_pk_mul_f32 v[56:57], v[56:57], v[66:67] op_sel_hi:[1,0]
	v_pk_mul_f32 v[54:55], v[54:55], v[66:67] op_sel_hi:[1,0]
	v_pk_mul_f32 v[52:53], v[52:53], v[66:67] op_sel_hi:[1,0]
	v_pk_mul_f32 v[50:51], v[50:51], v[66:67] op_sel_hi:[1,0]
	v_pk_mul_f32 v[48:49], v[48:49], v[66:67] op_sel_hi:[1,0]
	v_pk_mul_f32 v[46:47], v[46:47], v[66:67] op_sel_hi:[1,0]
	v_pk_mul_f32 v[44:45], v[44:45], v[66:67] op_sel_hi:[1,0]
	v_pk_mul_f32 v[42:43], v[42:43], v[66:67] op_sel_hi:[1,0]
	v_pk_mul_f32 v[40:41], v[40:41], v[66:67] op_sel_hi:[1,0]
	v_pk_mul_f32 v[38:39], v[38:39], v[66:67] op_sel_hi:[1,0]
	v_pk_mul_f32 v[36:37], v[36:37], v[66:67] op_sel_hi:[1,0]
	v_pk_mul_f32 v[34:35], v[34:35], v[66:67] op_sel_hi:[1,0]
	v_pk_mul_f32 v[32:33], v[32:33], v[66:67] op_sel_hi:[1,0]
	v_pk_mul_f32 v[30:31], v[30:31], v[66:67] op_sel_hi:[1,0]
	v_pk_mul_f32 v[28:29], v[28:29], v[66:67] op_sel_hi:[1,0]
	v_pk_mul_f32 v[26:27], v[26:27], v[66:67] op_sel_hi:[1,0]
	v_pk_mul_f32 v[24:25], v[24:25], v[66:67] op_sel_hi:[1,0]
	v_pk_mul_f32 v[22:23], v[22:23], v[66:67] op_sel_hi:[1,0]
	v_pk_mul_f32 v[20:21], v[20:21], v[66:67] op_sel_hi:[1,0]
	v_pk_mul_f32 v[18:19], v[18:19], v[66:67] op_sel_hi:[1,0]
	v_pk_mul_f32 v[16:17], v[16:17], v[66:67] op_sel_hi:[1,0]
	v_pk_mul_f32 v[14:15], v[14:15], v[66:67] op_sel_hi:[1,0]
	v_pk_mul_f32 v[12:13], v[12:13], v[66:67] op_sel_hi:[1,0]
	v_pk_mul_f32 v[10:11], v[10:11], v[66:67] op_sel_hi:[1,0]
	v_pk_mul_f32 v[8:9], v[8:9], v[66:67] op_sel_hi:[1,0]
	v_pk_mul_f32 v[6:7], v[6:7], v[66:67] op_sel_hi:[1,0]
	v_pk_mul_f32 v[4:5], v[4:5], v[66:67] op_sel_hi:[1,0]
	v_pk_mul_f32 v[2:3], v[2:3], v[66:67] op_sel_hi:[1,0]
	v_sub_f32_e32 v95, v95, v67
	v_sub_f32_e32 v94, v94, v67
	v_sub_f32_e32 v93, v93, v67
	v_sub_f32_e32 v92, v92, v67
	v_sub_f32_e32 v91, v91, v67
	v_sub_f32_e32 v90, v90, v67
	v_sub_f32_e32 v89, v89, v67
	v_sub_f32_e32 v88, v88, v67
	v_sub_f32_e32 v87, v87, v67
	v_sub_f32_e32 v86, v86, v67
	v_sub_f32_e32 v85, v85, v67
	v_sub_f32_e32 v84, v84, v67
	v_sub_f32_e32 v83, v83, v67
	v_sub_f32_e32 v82, v82, v67
	v_mul_f32_e32 v98, v98, v66

.LBB0_1308:
	v_exp_f32_e32 v82, v82
	v_exp_f32_e32 v83, v83
	s_addk_i32 s11, 0xdc00
	s_cmp_lg_u32 s10, 0
	s_cselect_b32 s4, s11, 0x4800
	v_add_f32_e32 v190, v82, v83
	v_cvt_pk_bf16_f32 v82, v82, v83
	v_exp_f32_e32 v83, v84
	v_exp_f32_e32 v84, v85
	v_add_f32_e32 v190, 0, v190
	v_add_f32_e32 v85, v83, v84
	v_cvt_pk_bf16_f32 v83, v83, v84
	v_exp_f32_e32 v84, v86
	v_exp_f32_e32 v86, v87
	v_add_f32_e32 v85, v85, v190
	v_add_f32_e32 v87, v84, v86
	v_add_f32_e32 v85, v87, v85
	v_cvt_pk_bf16_f32 v84, v84, v86
	v_exp_f32_e32 v86, v88
	v_exp_f32_e32 v87, v89
	s_nop 0
	v_add_f32_e32 v88, v86, v87
	v_add_f32_e32 v88, v88, v85
	v_cvt_pk_bf16_f32 v85, v86, v87
	v_exp_f32_e32 v86, v90
	v_exp_f32_e32 v87, v91
	s_nop 0
	v_add_f32_e32 v89, v86, v87
	v_add_f32_e32 v88, v89, v88
	v_cvt_pk_bf16_f32 v86, v86, v87
	v_exp_f32_e32 v87, v92
	v_exp_f32_e32 v89, v93
	s_nop 0
	v_add_f32_e32 v90, v87, v89
	v_add_f32_e32 v88, v90, v88
	v_cvt_pk_bf16_f32 v87, v87, v89
	v_exp_f32_e32 v89, v94
	v_exp_f32_e32 v90, v95
	s_nop 0
	v_add_f32_e32 v91, v89, v90
	v_add_f32_e32 v91, v91, v88
	v_cvt_pk_bf16_f32 v88, v89, v90
	v_exp_f32_e32 v89, v96
	v_exp_f32_e32 v90, v97
	s_nop 0
	v_add_f32_e32 v92, v89, v90
	v_add_f32_e32 v91, v92, v91
	v_cvt_pk_bf16_f32 v89, v89, v90
	v_lshl_add_u32 v90, s4, 1, v210
	v_add_f32_e32 v225, v98, v91
	v_add_u32_e32 v98, 0xc800, v90
	v_add_u32_e32 v227, 0xc810, v90
	v_add_u32_e32 v228, 0xc820, v90
	v_add_u32_e32 v229, 0xc830, v90
	ds_read_b64 v[90:91], v98
	ds_read_b64 v[92:93], v227
	ds_read_b64 v[94:95], v98 offset:2304
	ds_read_b64 v[96:97], v227 offset:2304
	s_waitcnt lgkmcnt(2)
	v_mfma_f32_32x32x16_bf16 v[50:65], v[90:93], v[82:85], v[50:65]
	ds_read_b64 v[190:191], v98 offset:4608
	ds_read_b64 v[192:193], v227 offset:4608
	v_max3_f32 v230, v66, s39, v67
	s_waitcnt lgkmcnt(2)
	v_mfma_f32_32x32x16_bf16 v[34:49], v[94:97], v[82:85], v[34:49]
	ds_read_b64 v[90:91], v98 offset:6912
	ds_read_b64 v[92:93], v227 offset:6912
	v_max3_f32 v98, v230, v68, v69
	s_waitcnt lgkmcnt(2)
	v_mfma_f32_32x32x16_bf16 v[18:33], v[190:193], v[82:85], v[18:33]
	ds_read_b64 v[94:95], v228
	ds_read_b64 v[96:97], v229
	v_max3_f32 v98, v98, v70, v71
	s_waitcnt lgkmcnt(2)
	v_mfma_f32_32x32x16_bf16 v[2:17], v[90:93], v[82:85], v[2:17]
	ds_read_b64 v[190:191], v228 offset:2304
	ds_read_b64 v[192:193], v229 offset:2304
	v_max3_f32 v90, v98, v72, v73
	s_waitcnt lgkmcnt(2)
	v_mfma_f32_32x32x16_bf16 v[50:65], v[94:97], v[86:89], v[50:65]
	ds_read_b64 v[82:83], v228 offset:4608
	ds_read_b64 v[84:85], v229 offset:4608
	v_max3_f32 v94, v90, v74, v75
	s_waitcnt lgkmcnt(2)
	v_mfma_f32_32x32x16_bf16 v[34:49], v[190:193], v[86:89], v[34:49]
	ds_read_b64 v[90:91], v228 offset:6912
	ds_read_b64 v[92:93], v229 offset:6912
	s_waitcnt lgkmcnt(2)
	v_mfma_f32_32x32x16_bf16 v[18:33], v[82:85], v[86:89], v[18:33]
	v_max3_f32 v82, v94, v76, v77
	s_waitcnt lgkmcnt(0)
	v_mfma_f32_32x32x16_bf16 v[2:17], v[90:93], v[86:89], v[2:17]
	v_max3_f32 v82, v82, v78, v79
	v_max3_f32 v82, v82, v80, v81
	v_mov_b32_e32 v83, v82
	s_nop 1
	v_permlane32_swap_b32_e32 v82, v83
	v_max_f32_e32 v82, v82, v83
	v_cmp_lt_f32_e32 vcc, s26, v82
	s_cbranch_vccz .LBB0_1310
	v_max_f32_e32 v82, v82, v82
	v_max_f32_e32 v83, 0, v82
	v_exp_f32_e64 v82, -v83
	v_add_f32_e32 v1, v1, v83
	v_sub_f32_e32 v81, v81, v83
	v_sub_f32_e32 v80, v80, v83
	v_pk_mul_f32 v[64:65], v[64:65], v[82:83] op_sel_hi:[1,0]
	v_pk_mul_f32 v[62:63], v[62:63], v[82:83] op_sel_hi:[1,0]
	v_pk_mul_f32 v[60:61], v[60:61], v[82:83] op_sel_hi:[1,0]
	v_pk_mul_f32 v[58:59], v[58:59], v[82:83] op_sel_hi:[1,0]
	v_pk_mul_f32 v[56:57], v[56:57], v[82:83] op_sel_hi:[1,0]
	v_pk_mul_f32 v[54:55], v[54:55], v[82:83] op_sel_hi:[1,0]
	v_pk_mul_f32 v[52:53], v[52:53], v[82:83] op_sel_hi:[1,0]
	v_pk_mul_f32 v[50:51], v[50:51], v[82:83] op_sel_hi:[1,0]
	v_pk_mul_f32 v[48:49], v[48:49], v[82:83] op_sel_hi:[1,0]
	v_pk_mul_f32 v[46:47], v[46:47], v[82:83] op_sel_hi:[1,0]
	v_pk_mul_f32 v[44:45], v[44:45], v[82:83] op_sel_hi:[1,0]
	v_pk_mul_f32 v[42:43], v[42:43], v[82:83] op_sel_hi:[1,0]
	v_pk_mul_f32 v[40:41], v[40:41], v[82:83] op_sel_hi:[1,0]
	v_pk_mul_f32 v[38:39], v[38:39], v[82:83] op_sel_hi:[1,0]
	v_pk_mul_f32 v[36:37], v[36:37], v[82:83] op_sel_hi:[1,0]
	v_pk_mul_f32 v[34:35], v[34:35], v[82:83] op_sel_hi:[1,0]
	v_pk_mul_f32 v[32:33], v[32:33], v[82:83] op_sel_hi:[1,0]
	v_pk_mul_f32 v[30:31], v[30:31], v[82:83] op_sel_hi:[1,0]
	v_pk_mul_f32 v[28:29], v[28:29], v[82:83] op_sel_hi:[1,0]
	v_pk_mul_f32 v[26:27], v[26:27], v[82:83] op_sel_hi:[1,0]
	v_pk_mul_f32 v[24:25], v[24:25], v[82:83] op_sel_hi:[1,0]
	v_pk_mul_f32 v[22:23], v[22:23], v[82:83] op_sel_hi:[1,0]
	v_pk_mul_f32 v[20:21], v[20:21], v[82:83] op_sel_hi:[1,0]
	v_pk_mul_f32 v[18:19], v[18:19], v[82:83] op_sel_hi:[1,0]
	v_pk_mul_f32 v[16:17], v[16:17], v[82:83] op_sel_hi:[1,0]
	v_pk_mul_f32 v[14:15], v[14:15], v[82:83] op_sel_hi:[1,0]
	v_pk_mul_f32 v[12:13], v[12:13], v[82:83] op_sel_hi:[1,0]
	v_pk_mul_f32 v[10:11], v[10:11], v[82:83] op_sel_hi:[1,0]
	v_pk_mul_f32 v[8:9], v[8:9], v[82:83] op_sel_hi:[1,0]
	v_pk_mul_f32 v[6:7], v[6:7], v[82:83] op_sel_hi:[1,0]
	v_pk_mul_f32 v[4:5], v[4:5], v[82:83] op_sel_hi:[1,0]
	v_pk_mul_f32 v[2:3], v[2:3], v[82:83] op_sel_hi:[1,0]
	v_sub_f32_e32 v79, v79, v83
	v_sub_f32_e32 v78, v78, v83
	v_sub_f32_e32 v77, v77, v83
	v_sub_f32_e32 v76, v76, v83
	v_sub_f32_e32 v75, v75, v83
	v_sub_f32_e32 v74, v74, v83
	v_sub_f32_e32 v73, v73, v83
	v_sub_f32_e32 v72, v72, v83
	v_sub_f32_e32 v71, v71, v83
	v_sub_f32_e32 v70, v70, v83
	v_sub_f32_e32 v69, v69, v83
	v_sub_f32_e32 v68, v68, v83
	v_sub_f32_e32 v67, v67, v83
	v_sub_f32_e32 v66, v66, v83
	v_mul_f32_e32 v225, v225, v82
